# stick-breaking items: XCD-aware static order (each XCD slot takes all query tiles of one head, so that head K/V image stays in its L2)
# baseline (speedup 1.0000x reference)
; #define OPQ(x) asm volatile("" : "+s"(x))
; #define OPQP(T, x) do { unsigned long long xi_ = (unsigned long long)(x); asm volatile("" : "+s"(xi_)); x = (T*)(__attribute__((address_space(1))) T*)xi_; } while (0)
; __global__ void __launch_bounds__(512, 2) mega_fwd(Args args) {
;     ...
;                 if (ph == 0) { unsigned char* w2 = ws; float* o2 = out; int l2 = l; OPQP(unsigned char, w2); OPQP(float, o2); OPQ(l2);
;                     const unsigned long long* tab2 = (const unsigned long long*)w2; unsigned* ctr2 = (unsigned*)(w2 + WS_CTR) + 2 * l2 + 1;
;                     unsigned wq = 0; if (lane == 0) wq = atomicAdd(ctr2, 1u); int w = __builtin_amdgcn_readfirstlane(wq);
;                     while (w < 4352) { unsigned wn = 0; if (lane == 0) wn = atomicAdd(ctr2, 1u);
.LBB0_1666:
	s_andn2_b64 vcc, exec, s[80:81]
	v_readlane_b32 s81, v254, 37
	s_cbranch_vccnz .LBB0_1696
	v_readlane_b32 s0, v253, 38
	v_readlane_b32 s1, v253, 39
	v_readlane_b32 s2, v253, 40
	v_readlane_b32 s3, v253, 41
	s_mov_b64 s[4:5], s[0:1]
	v_readlane_b32 s0, v254, 42
	s_mov_b64 s[8:9], s[2:3]
	s_mov_b32 s2, s0
	s_lshl_b32 s0, s2, 1
	s_ashr_i32 s1, s0, 31
	s_lshl_b64 s[0:1], s[0:1], 2
	s_add_u32 s0, s8, s0
	s_addc_u32 s1, s9, s1
	s_add_u32 s10, s0, 0x14004
	s_addc_u32 s11, s1, 0
	s_waitcnt vmcnt(0)
	v_lshrrev_b32_e32 v0, 6, v222
	s_and_b32 s3, s81, 7
	s_lshl_b32 s3, s3, 5
	v_readfirstlane_b32 s27, v0
	s_lshr_b32 s98, s81, 3
	s_add_i32 s3, s3, s98
	s_lshl_b32 s3, s3, 3
	s_add_i32 s100, s3, s27
	s_addk_i32 s100, 0x100
	s_cmp_eq_u32 s27, 0
	s_cselect_b32 s27, s81, s100

; #define GPTR(p) gptr_(p)
; __global__ void __launch_bounds__(512, 2) mega_fwd(Args args) {
;     ...
;                     while (w < 4352) { unsigned wn = 0; if (lane == 0) wn = atomicAdd(ctr2, 1u);
;                         int lane2 = lane; asm volatile("" : "+v"(lane2));
;                         if (w < 256) sb_item<true>(4096 + w, l2, (const float*)(w2 + WS_PROJ), o2 + O_KP + (size_t)l2 * NPROMPT * 512, o2 + O_VP + (size_t)l2 * NPROMPT * 512,
;                                                     o2 + O_KS + (size_t)l2 * 262144, o2 + O_VS + (size_t)l2 * 262144, GPTR(tab2[3]), GPTR(tab2[4]), (const bf16_t*)(w2 + WS_VT), (const bf16_t*)(w2 + WS_KB), (float*)(w2 + WS_OSB), lane2);
;                         else sb_item<false>(w - 256, l2, (const float*)(w2 + WS_PROJ), o2 + O_KP + (size_t)l2 * NPROMPT * 512, o2 + O_VP + (size_t)l2 * NPROMPT * 512,
;                                                     o2 + O_KS + (size_t)l2 * 262144, o2 + O_VS + (size_t)l2 * 262144, GPTR(tab2[3]), GPTR(tab2[4]), (const bf16_t*)(w2 + WS_VT), (const bf16_t*)(w2 + WS_KB), (float*)(w2 + WS_OSB), lane2);
;                         w = __builtin_amdgcn_readfirstlane(wn); } }
.LBB0_1674:
	s_add_i32 s98, s27, 0x800
	s_cmpk_lt_u32 s27, 0x100
	s_cselect_b32 s98, s100, s98
	s_cmpk_ge_u32 s98, 0x1100
	s_cselect_b32 s98, 0x7fff, s98
	v_mov_b32_e32 v160, s98
